# nt_loads_p0a_only
# baseline (speedup 1.0000x reference)
.LBB0_34:
	s_lshl_b32 s28, s3, 1
	s_lshl_b32 s29, s11, 1
	v_or_b32_e32 v15, s28, v1
	v_or_b32_e32 v77, s29, v2
	s_add_i32 s30, s28, 4
	s_add_i32 s31, s29, 4
	s_add_i32 s34, s28, 8
	s_add_i32 s35, s29, 8
	s_add_i32 s36, s28, 12
	s_add_i32 s37, s29, 12
	s_add_i32 s38, s28, 16
	s_add_i32 s39, s29, 16
	s_add_i32 s40, s28, 20
	s_add_i32 s41, s29, 20
	s_add_i32 s42, s28, 24
	s_add_i32 s43, s29, 24
	s_add_i32 s28, s28, 28
	s_add_i32 s29, s29, 28
	v_add_u32_e32 v16, s9, v15
	v_add_u32_e32 v18, s10, v77
	v_or_b32_e32 v79, s30, v1
	v_or_b32_e32 v80, s31, v2
	v_or_b32_e32 v81, s34, v1
	v_or_b32_e32 v82, s35, v2
	v_or_b32_e32 v83, s36, v1
	v_or_b32_e32 v84, s37, v2
	v_or_b32_e32 v85, s38, v1
	v_or_b32_e32 v86, s39, v2
	v_or_b32_e32 v87, s40, v1
	v_or_b32_e32 v88, s41, v2
	v_or_b32_e32 v89, s42, v1
	v_or_b32_e32 v90, s43, v2
	v_or_b32_e32 v91, s28, v1
	v_or_b32_e32 v92, s29, v2
	v_ashrrev_i32_e32 v23, 31, v18
	v_ashrrev_i32_e32 v21, 31, v16
	v_mad_u64_u32 v[16:17], s[28:29], s12, v16, 0
	v_mad_u64_u32 v[18:19], s[28:29], s27, v18, 0
	v_add_u32_e32 v24, s9, v79
	v_add_u32_e32 v26, s10, v80
	v_add_u32_e32 v28, s9, v81
	v_add_u32_e32 v30, s10, v82
	v_add_u32_e32 v32, s9, v83
	v_add_u32_e32 v34, s10, v84
	v_add_u32_e32 v36, s9, v85
	v_add_u32_e32 v38, s10, v86
	v_add_u32_e32 v40, s9, v87
	v_add_u32_e32 v42, s10, v88
	v_add_u32_e32 v44, s9, v89
	v_add_u32_e32 v46, s10, v90
	v_add_u32_e32 v48, s9, v91
	v_add_u32_e32 v50, s10, v92
	v_mov_b32_e32 v20, v17
	v_mov_b32_e32 v22, v19
	v_ashrrev_i32_e32 v53, 31, v26
	v_ashrrev_i32_e32 v55, 31, v24
	v_mad_u64_u32 v[24:25], s[28:29], s12, v24, 0
	v_mad_u64_u32 v[26:27], s[28:29], s27, v26, 0
	v_ashrrev_i32_e32 v57, 31, v30
	v_ashrrev_i32_e32 v59, 31, v28
	v_mad_u64_u32 v[28:29], s[28:29], s12, v28, 0
	v_mad_u64_u32 v[30:31], s[28:29], s27, v30, 0
	v_ashrrev_i32_e32 v61, 31, v34
	v_ashrrev_i32_e32 v63, 31, v32
	v_mad_u64_u32 v[32:33], s[28:29], s12, v32, 0
	v_mad_u64_u32 v[34:35], s[28:29], s27, v34, 0
	v_ashrrev_i32_e32 v65, 31, v38
	v_ashrrev_i32_e32 v67, 31, v36
	v_mad_u64_u32 v[36:37], s[28:29], s12, v36, 0
	v_mad_u64_u32 v[38:39], s[28:29], s27, v38, 0
	v_ashrrev_i32_e32 v69, 31, v42
	v_ashrrev_i32_e32 v71, 31, v40
	v_mad_u64_u32 v[40:41], s[28:29], s12, v40, 0
	v_mad_u64_u32 v[42:43], s[28:29], s27, v42, 0
	v_ashrrev_i32_e32 v73, 31, v46
	v_ashrrev_i32_e32 v75, 31, v44
	v_mad_u64_u32 v[44:45], s[28:29], s12, v44, 0
	v_mad_u64_u32 v[46:47], s[28:29], s27, v46, 0
	v_ashrrev_i32_e32 v93, 31, v50
	v_ashrrev_i32_e32 v94, 31, v48
	v_mad_u64_u32 v[48:49], s[28:29], s12, v48, 0
	v_mad_u64_u32 v[50:51], s[28:29], s27, v50, 0
	v_mad_u64_u32 v[20:21], s[28:29], s12, v21, v[20:21]
	v_mad_u64_u32 v[22:23], s[28:29], s27, v23, v[22:23]
	v_mov_b32_e32 v52, v25
	v_mov_b32_e32 v54, v27
	v_mov_b32_e32 v56, v29
	v_mov_b32_e32 v58, v31
	v_mov_b32_e32 v60, v33
	v_mov_b32_e32 v62, v35
	v_mov_b32_e32 v64, v37
	v_mov_b32_e32 v66, v39
	v_mov_b32_e32 v68, v41
	v_mov_b32_e32 v70, v43
	v_mov_b32_e32 v72, v45
	v_mov_b32_e32 v74, v47
	v_mov_b32_e32 v76, v49
	v_mov_b32_e32 v78, v51
	v_mov_b32_e32 v17, v20
	v_mov_b32_e32 v19, v22
	v_mad_u64_u32 v[20:21], s[28:29], s12, v55, v[52:53]
	v_mad_u64_u32 v[22:23], s[28:29], s27, v53, v[54:55]
	v_mad_u64_u32 v[52:53], s[28:29], s12, v59, v[56:57]
	v_mad_u64_u32 v[54:55], s[28:29], s27, v57, v[58:59]
	v_mad_u64_u32 v[56:57], s[28:29], s12, v63, v[60:61]
	v_mad_u64_u32 v[58:59], s[28:29], s27, v61, v[62:63]
	v_mad_u64_u32 v[60:61], s[28:29], s12, v67, v[64:65]
	v_mad_u64_u32 v[62:63], s[28:29], s27, v65, v[66:67]
	v_mad_u64_u32 v[64:65], s[28:29], s12, v71, v[68:69]
	v_mad_u64_u32 v[66:67], s[28:29], s27, v69, v[70:71]
	v_mad_u64_u32 v[68:69], s[28:29], s12, v75, v[72:73]
	v_mad_u64_u32 v[70:71], s[28:29], s27, v73, v[74:75]
	v_mad_u64_u32 v[72:73], s[28:29], s12, v94, v[76:77]
	v_mad_u64_u32 v[74:75], s[28:29], s27, v93, v[78:79]
	v_mov_b32_e32 v25, v20
	v_mov_b32_e32 v27, v22
	v_mov_b32_e32 v29, v52
	v_mov_b32_e32 v31, v54
	v_mov_b32_e32 v33, v56
	v_mov_b32_e32 v35, v58
	v_mov_b32_e32 v37, v60
	v_mov_b32_e32 v39, v62
	v_mov_b32_e32 v41, v64
	v_mov_b32_e32 v43, v66
	v_mov_b32_e32 v45, v68
	v_mov_b32_e32 v47, v70
	v_lshl_add_u64 v[18:19], v[18:19], 2, v[10:11]
	v_mov_b32_e32 v49, v72
	v_mov_b32_e32 v51, v74
	v_lshl_add_u64 v[16:17], v[16:17], 2, v[10:11]
	v_lshl_add_u64 v[20:21], v[26:27], 2, v[10:11]
	v_lshl_add_u64 v[22:23], v[24:25], 2, v[10:11]
	v_lshl_add_u64 v[24:25], v[30:31], 2, v[10:11]
	v_lshl_add_u64 v[26:27], v[28:29], 2, v[10:11]
	v_lshl_add_u64 v[28:29], v[34:35], 2, v[10:11]
	v_lshl_add_u64 v[30:31], v[32:33], 2, v[10:11]
	v_lshl_add_u64 v[32:33], v[38:39], 2, v[10:11]
	v_lshl_add_u64 v[34:35], v[36:37], 2, v[10:11]
	v_lshl_add_u64 v[36:37], v[42:43], 2, v[10:11]
	v_lshl_add_u64 v[38:39], v[40:41], 2, v[10:11]
	v_lshl_add_u64 v[40:41], v[46:47], 2, v[10:11]
	v_lshl_add_u64 v[42:43], v[44:45], 2, v[10:11]
	v_lshl_add_u64 v[44:45], v[50:51], 2, v[10:11]
	v_lshl_add_u64 v[46:47], v[48:49], 2, v[10:11]
	global_load_dword v48, v[18:19], off nt
	global_load_dword v49, v[16:17], off nt
	global_load_dword v50, v[20:21], off nt
	global_load_dword v51, v[22:23], off nt
	global_load_dword v52, v[24:25], off nt
	global_load_dword v53, v[26:27], off nt
	global_load_dword v54, v[28:29], off nt
	global_load_dword v55, v[30:31], off nt
	global_load_dword v56, v[32:33], off nt
	global_load_dword v57, v[34:35], off nt
	global_load_dword v58, v[36:37], off nt
	global_load_dword v59, v[38:39], off nt
	global_load_dword v60, v[40:41], off nt
	global_load_dword v61, v[42:43], off nt
	global_load_dword v62, v[44:45], off nt
	global_load_dword v63, v[46:47], off nt
	s_add_i32 s11, s11, 16
	s_add_i32 s3, s3, 16
	s_add_i32 s13, s13, -16
	v_mad_u64_u32 v[16:17], s[28:29], v77, s26, v[6:7]
	s_cmp_lg_u32 s13, 0
	v_mad_u64_u32 v[18:19], s[28:29], v15, s26, v[6:7]
	v_mad_u64_u32 v[20:21], s[28:29], v80, s26, v[6:7]
	v_mad_u64_u32 v[22:23], s[28:29], v79, s26, v[6:7]
	v_mad_u64_u32 v[24:25], s[28:29], v82, s26, v[6:7]
	v_mad_u64_u32 v[26:27], s[28:29], v81, s26, v[6:7]
	v_mad_u64_u32 v[28:29], s[28:29], v84, s26, v[6:7]
	v_mad_u64_u32 v[30:31], s[28:29], v83, s26, v[6:7]
	v_mad_u64_u32 v[32:33], s[28:29], v86, s26, v[6:7]
	v_mad_u64_u32 v[34:35], s[28:29], v85, s26, v[6:7]
	v_mad_u64_u32 v[36:37], s[28:29], v88, s26, v[6:7]
	v_mad_u64_u32 v[38:39], s[28:29], v87, s26, v[6:7]
	v_mad_u64_u32 v[40:41], s[28:29], v90, s26, v[6:7]
	v_mad_u64_u32 v[42:43], s[28:29], v89, s26, v[6:7]
	v_mad_u64_u32 v[44:45], s[28:29], v92, s26, v[6:7]
	v_mad_u64_u32 v[46:47], s[28:29], v91, s26, v[6:7]
	s_waitcnt vmcnt(15)
	ds_write_b32 v16, v48
	s_waitcnt vmcnt(14)
	ds_write_b32 v18, v49
	s_waitcnt vmcnt(13)
	ds_write_b32 v20, v50
	s_waitcnt vmcnt(12)
	ds_write_b32 v22, v51
	s_waitcnt vmcnt(11)
	ds_write_b32 v24, v52
	s_waitcnt vmcnt(10)
	ds_write_b32 v26, v53
	s_waitcnt vmcnt(9)
	ds_write_b32 v28, v54
	s_waitcnt vmcnt(8)
	ds_write_b32 v30, v55
	s_waitcnt vmcnt(7)
	ds_write_b32 v32, v56
	s_waitcnt vmcnt(6)
	ds_write_b32 v34, v57
	s_waitcnt vmcnt(5)
	ds_write_b32 v36, v58
	s_waitcnt vmcnt(4)
	ds_write_b32 v38, v59
	s_waitcnt vmcnt(3)
	ds_write_b32 v40, v60
	s_waitcnt vmcnt(2)
	ds_write_b32 v42, v61
	s_waitcnt vmcnt(1)
	ds_write_b32 v44, v62
	s_waitcnt vmcnt(0)
	ds_write_b32 v46, v63
	s_cbranch_scc1 .LBB0_34
	s_lshl_b64 s[6:7], s[6:7], 1
	s_waitcnt lgkmcnt(0)
	s_add_u32 s3, s4, s6
	s_addc_u32 s6, s5, s7
	s_ashr_i32 s11, s10, 31
	ds_read2_b32 v[10:11], v7 offset1:33
	s_lshl_b64 s[4:5], s[10:11], 1
	s_waitcnt lgkmcnt(0)
	v_cvt_pk_bf16_f32 v16, v10, v11
	ds_read2_b32 v[10:11], v7 offset0:66 offset1:99
	s_add_u32 s4, s3, s4
	s_waitcnt lgkmcnt(0)
	v_cvt_pk_bf16_f32 v17, v10, v11
	ds_read2_b32 v[10:11], v7 offset0:132 offset1:165
	v_or_b32_e32 v15, s8, v3
	s_addc_u32 s5, s6, s5
	v_mul_hi_i32_i24_e32 v21, s2, v15
	v_mul_i32_i24_e32 v20, s2, v15
	s_waitcnt lgkmcnt(0)
	v_cvt_pk_bf16_f32 v18, v10, v11
	ds_read2_b32 v[10:11], v7 offset0:198 offset1:231
	v_lshl_add_u64 v[22:23], s[4:5], 0, v[4:5]
	s_waitcnt lgkmcnt(0)
	v_cvt_pk_bf16_f32 v19, v10, v11
	ds_read2_b32 v[10:11], v7 offset0:8 offset1:41
	v_lshl_add_u64 v[20:21], v[20:21], 1, v[22:23]
	global_store_dwordx4 v[20:21], v[16:19], off
	v_or_b32_e32 v15, s8, v12
	v_mul_hi_i32_i24_e32 v21, s2, v15
	s_waitcnt lgkmcnt(0)
	v_cvt_pk_bf16_f32 v16, v10, v11
	ds_read2_b32 v[10:11], v7 offset0:74 offset1:107
	s_waitcnt lgkmcnt(0)
	v_cvt_pk_bf16_f32 v17, v10, v11
	ds_read2_b32 v[10:11], v7 offset0:140 offset1:173
	s_waitcnt lgkmcnt(0)
	v_cvt_pk_bf16_f32 v18, v10, v11
	ds_read2_b32 v[10:11], v7 offset0:206 offset1:239
	v_mul_i32_i24_e32 v20, s2, v15
	s_waitcnt lgkmcnt(0)
	v_cvt_pk_bf16_f32 v19, v10, v11
	ds_read2_b32 v[10:11], v7 offset0:16 offset1:49
	v_lshl_add_u64 v[20:21], v[20:21], 1, v[22:23]
	global_store_dwordx4 v[20:21], v[16:19], off
	v_or_b32_e32 v15, s8, v13
	v_mul_hi_i32_i24_e32 v21, s2, v15
	s_waitcnt lgkmcnt(0)
	v_cvt_pk_bf16_f32 v16, v10, v11
	ds_read2_b32 v[10:11], v7 offset0:82 offset1:115
	s_waitcnt lgkmcnt(0)
	v_cvt_pk_bf16_f32 v17, v10, v11
	ds_read2_b32 v[10:11], v7 offset0:148 offset1:181
	s_waitcnt lgkmcnt(0)
	v_cvt_pk_bf16_f32 v18, v10, v11
	ds_read2_b32 v[10:11], v7 offset0:214 offset1:247
	v_mul_i32_i24_e32 v20, s2, v15
	s_waitcnt lgkmcnt(0)
	v_cvt_pk_bf16_f32 v19, v10, v11
	ds_read2_b32 v[10:11], v7 offset0:24 offset1:57
	v_lshl_add_u64 v[20:21], v[20:21], 1, v[22:23]
	v_or_b32_e32 v15, s8, v14
	global_store_dwordx4 v[20:21], v[16:19], off
	v_mul_hi_i32_i24_e32 v21, s2, v15
	v_mul_i32_i24_e32 v20, s2, v15
	s_waitcnt lgkmcnt(0)
	v_cvt_pk_bf16_f32 v16, v10, v11
	ds_read2_b32 v[10:11], v7 offset0:90 offset1:123
	s_waitcnt lgkmcnt(0)
	v_cvt_pk_bf16_f32 v17, v10, v11
	ds_read2_b32 v[10:11], v7 offset0:156 offset1:189
	v_lshl_add_u64 v[20:21], v[20:21], 1, v[22:23]
	s_waitcnt lgkmcnt(0)
	v_cvt_pk_bf16_f32 v18, v10, v11
	ds_read2_b32 v[10:11], v7 offset0:222 offset1:255
	s_waitcnt lgkmcnt(0)
	v_cvt_pk_bf16_f32 v19, v10, v11
	global_store_dwordx4 v[20:21], v[16:19], off
	s_waitcnt lgkmcnt(0)
	s_add_i32 s14, s14, s15
	s_cmp_lt_i32 s14, 0x1e800
	s_cbranch_scc1 .LBB0_11
	s_branch .LBB0_37
